# hand-scheduled diff-attention tile loop: fold -m into MFMA C-init, tree max, permlane swap, exp/PV interleave
# speedup vs baseline: 1.0263x; 1.0263x over previous
; DI int opaque_tid() { int t = threadIdx.x; asm volatile("" : "+v"(t)); return t; }
; template <int DV, bool NA> ...
;   const int tid = opaque_tid(), lane = tid & 63;
;   const int h = lane >> 5, r = lane & 31;
;   bf16x8 q[4];
; #pragma unroll
;   for (int ks = 0; ks < 4; ++ks) q[ks] = *(const bf16x8*)(Qp + ks * 16 + h * 8);
; #pragma unroll
;   for (int mv = 0; mv < DV / 32; ++mv)
; #pragma unroll
;     for (int i = 0; i < 16; ++i) o[mv][i] = 0.f;
;   float m_run = -INFINITY, l_run = 0.f;
;   const int lr = tid >> 3, lc = tid & 7;
;   const int wsw = lr * 128 + ((lc ^ ((lr >> 1) & 7)) << 4);
;   u32x4 rk, rv[DV / 64];
;   auto gload = [&](int ti) {
;     const size_t key0 = (size_t)(tile0 + ti) * 64;
;     rk = *(const u32x4*)(Kb + (key0 + lr) * ldk + lc * 8);
; #pragma unroll
;     for (int i = 0; i < DV / 64; ++i) rv[i] = *(const u32x4*)(Vt + (size_t)(lr + 64 * i) * S + key0 + lc * 8);
;   };
;   auto swrite = [&](int st) {
;     char* ks_ = lds + st * ATT_STAGE;
;     *(u32x4*)(ks_ + wsw) = rk;
; #pragma unroll
;     for (int i = 0; i < DV / 64; ++i) *(u32x4*)(ks_ + 8192 + i * 8192 + wsw) = rv[i];
;   };
;   const int pr = (r & 0x13) | ((r & 4) << 1) | ((r & 8) >> 1);
;   const int ksw = (pr >> 1) & 7;
;   const int vsw = (r >> 1) & 7;
;   const int cs_ = NA ? min(max(qc - 8, 0), 48) : 0;
;   __syncthreads();
;   gload(0);
;   swrite(0);
;   if (ntiles > 1) gload(1);
;   __syncthreads();
; #pragma unroll 2
;   for (int ti = 0; ti < ntiles; ++ti) {
;     if (ti + 1 < ntiles) {
;       swrite((ti + 1) & 1);
;       if (ti + 2 < ntiles) gload(ti + 2);
.LBB0_294:
	v_or_b32_e32 v0, s20, v198
	v_mov_b32_e32 v26, v204
	v_lshlrev_b64 v[2:3], 1, v[0:1]
	v_lshl_add_u64 v[4:5], v[162:163], 0, v[2:3]
	v_bfe_u32 v27, v26, 5, 1
	v_lshl_add_u64 v[2:3], v[160:161], 0, v[2:3]
	v_lshlrev_b32_e32 v0, 4, v27
	v_ashrrev_i32_e32 v14, 3, v26
	v_lshlrev_b32_e32 v28, 4, v26
	v_lshl_add_u64 v[4:5], v[4:5], 0, v[0:1]
	v_ashrrev_i32_e32 v15, 31, v14
	v_mad_i64_i32 v[2:3], s[22:23], v14, s96, v[2:3]
	v_and_b32_e32 v0, 0x70, v28
	v_add_u32_e32 v10, 64, v14
	v_lshl_add_u64 v[16:17], v[2:3], 0, v[0:1]
	v_lshlrev_b64 v[2:3], v176, v[14:15]
	v_ashrrev_i32_e32 v11, 31, v10
	v_lshlrev_b64 v[18:19], 1, v[2:3]
	v_lshlrev_b64 v[10:11], v176, v[10:11]
	v_lshl_add_u64 v[2:3], v[164:165], 0, v[18:19]
	v_lshlrev_b64 v[22:23], 1, v[10:11]
	global_load_dwordx4 v[124:127], v[4:5], off
	global_load_dwordx4 v[120:123], v[4:5], off offset:32
	global_load_dwordx4 v[116:119], v[4:5], off offset:64
	global_load_dwordx4 v[112:115], v[4:5], off offset:96
	s_barrier
	v_lshl_add_u64 v[20:21], v[2:3], 0, v[0:1]
	global_load_dwordx4 v[2:5], v[16:17], off offset:1024
	global_load_dwordx4 v[6:9], v[20:21], off
	v_lshl_add_u64 v[10:11], v[164:165], 0, v[22:23]
	v_lshl_add_u64 v[24:25], v[10:11], 0, v[0:1]
	v_add_co_u32_e32 v16, vcc, s97, v16
	global_load_dwordx4 v[10:13], v[24:25], off
	s_nop 0
	v_addc_co_u32_e32 v17, vcc, 0, v17, vcc
	global_load_dwordx4 v[132:135], v[20:21], off offset:128
	global_load_dwordx4 v[128:131], v[16:17], off offset:1024
	global_load_dwordx4 v[136:139], v[24:25], off offset:128
	v_lshlrev_b32_e32 v15, 1, v26
	v_lshrrev_b32_e32 v20, 1, v26
	v_lshrrev_b32_e32 v16, 5, v26
	v_and_b32_e32 v17, 19, v26
	v_bfe_u32 v21, v26, 1, 3
	v_lshlrev_b32_e32 v24, 7, v26
	v_xor_b32_e32 v26, v28, v26
	v_and_b32_e32 v28, 8, v15
	v_and_b32_e32 v20, 4, v20
	v_bitop3_b32 v16, v16, v21, 1 bitop3:0x6c
	v_or3_b32 v17, v28, v17, v20
	v_lshlrev_b32_e32 v25, 7, v14
	v_and_b32_e32 v178, 0xf80, v24
	v_or_b32_e32 v24, 4, v27
	v_or_b32_e32 v29, 2, v27
	v_or_b32_e32 v30, 6, v27
	v_bitop3_b32 v31, v27, v21, 2 bitop3:0x36
	v_bitop3_b32 v32, v27, v21, 4 bitop3:0x36
	v_bitop3_b32 v21, v27, v21, 6 bitop3:0x36
	v_lshlrev_b32_e32 v195, 4, v16
	v_lshrrev_b32_e32 v16, 1, v17
	v_mad_i64_i32 v[14:15], s[22:23], v14, s96, 0
	v_and_or_b32 v203, v26, s66, v25
	v_lshlrev_b32_e32 v179, 4, v21
	v_lshlrev_b32_e32 v228, 7, v17
	v_bitop3_b32 v20, v16, v27, 7 bitop3:0x6c
	v_bitop3_b32 v21, v16, v29, 7 bitop3:0x6c
	v_bitop3_b32 v24, v16, v24, 7 bitop3:0x6c
	v_bitop3_b32 v25, v16, v30, 7 bitop3:0x6c
	v_lshl_add_u64 v[16:17], v[0:1], 0, v[18:19]
	v_or_b32_e32 v14, v14, v0
	v_lshl_add_u64 v[170:171], v[166:167], 0, v[16:17]
	v_lshl_add_u64 v[16:17], v[0:1], 0, v[22:23]
	v_add_u32_e32 v0, s20, v198
	s_waitcnt vmcnt(18)
	v_lshlrev_b32_e32 v183, 4, v31
	v_lshlrev_b32_e32 v181, 4, v32
	v_lshlrev_b32_e32 v229, 4, v20
	v_lshlrev_b32_e32 v202, 4, v21
	v_lshlrev_b32_e32 v201, 4, v24
	v_lshlrev_b32_e32 v200, 4, v25
	v_lshl_add_u64 v[172:173], v[166:167], 0, v[16:17]
	v_mov_b32_e32 v180, 0
	v_mov_b32_e32 v182, 0xff800000
	s_mov_b64 s[20:21], 0
	s_mov_b32 s31, 0
	s_waitcnt vmcnt(5)
	ds_write_b128 v203, v[2:5]
	s_waitcnt vmcnt(4)
	ds_write_b128 v203, v[6:9] offset:8192
	s_waitcnt vmcnt(3)
	ds_write_b128 v203, v[10:13] offset:16384
	v_lshl_add_u64 v[2:3], v[0:1], 1, v[14:15]
	v_mov_b32_e32 v14, v1
	v_mov_b32_e32 v15, v1
	v_lshl_add_u64 v[174:175], v[168:169], 0, v[2:3]
	v_mov_b32_e32 v0, v1
	v_mov_b32_e32 v2, v1
	v_mov_b32_e32 v3, v1
	v_mov_b32_e32 v4, v1
	v_mov_b32_e32 v5, v1
	v_mov_b32_e32 v6, v1
	v_mov_b32_e32 v7, v1
	v_mov_b32_e32 v8, v1
	v_mov_b32_e32 v9, v1
	v_mov_b32_e32 v10, v1
	v_mov_b32_e32 v11, v1
	v_mov_b32_e32 v12, v1
	v_mov_b32_e32 v13, v1
	v_mov_b64_e32 v[30:31], v[14:15]
	v_mov_b64_e32 v[46:47], v[14:15]
	v_mov_b64_e32 v[62:63], v[14:15]
	v_mov_b64_e32 v[78:79], v[14:15]
	v_mov_b64_e32 v[28:29], v[12:13]
	v_mov_b64_e32 v[26:27], v[10:11]
	v_mov_b64_e32 v[24:25], v[8:9]
	v_mov_b64_e32 v[22:23], v[6:7]
	v_mov_b64_e32 v[20:21], v[4:5]
	v_mov_b64_e32 v[18:19], v[2:3]
	v_mov_b64_e32 v[16:17], v[0:1]
	v_mov_b64_e32 v[44:45], v[12:13]
	v_mov_b64_e32 v[42:43], v[10:11]
	v_mov_b64_e32 v[40:41], v[8:9]
	v_mov_b64_e32 v[38:39], v[6:7]
	v_mov_b64_e32 v[36:37], v[4:5]
	v_mov_b64_e32 v[34:35], v[2:3]
	v_mov_b64_e32 v[32:33], v[0:1]
	v_mov_b64_e32 v[60:61], v[12:13]
	v_mov_b64_e32 v[58:59], v[10:11]
	v_mov_b64_e32 v[56:57], v[8:9]
	v_mov_b64_e32 v[54:55], v[6:7]
	v_mov_b64_e32 v[52:53], v[4:5]
	v_mov_b64_e32 v[50:51], v[2:3]
	v_mov_b64_e32 v[48:49], v[0:1]
	v_mov_b64_e32 v[76:77], v[12:13]
	v_mov_b64_e32 v[74:75], v[10:11]
	v_mov_b64_e32 v[72:73], v[8:9]
	v_mov_b64_e32 v[70:71], v[6:7]
	v_mov_b64_e32 v[68:69], v[4:5]
	v_mov_b64_e32 v[66:67], v[2:3]
	v_mov_b64_e32 v[64:65], v[0:1]
	v_mov_b32_e32 v182, 0
	s_mov_b32 s100, 0xff800000
	s_mov_b32 s101, 0xff800000
	v_mov_b32_e32 v234, 0
	v_mov_b32_e32 v235, 0
	v_mov_b32_e32 v236, 0
	v_mov_b32_e32 v237, 0
	v_mov_b32_e32 v238, 0
	v_mov_b32_e32 v239, 0
	v_mov_b32_e32 v240, 0
	v_mov_b32_e32 v241, 0
	v_mov_b32_e32 v242, 0
	v_mov_b32_e32 v243, 0
	v_mov_b32_e32 v244, 0
	v_mov_b32_e32 v245, 0
	v_mov_b32_e32 v246, 0
	v_mov_b32_e32 v247, 0
	v_mov_b32_e32 v248, 0
	v_mov_b32_e32 v249, 0
	s_waitcnt lgkmcnt(0)
	s_barrier
	s_branch .LBB0_296
.LBB0_296:
	s_add_i32 s29, s31, 1
	s_bitcmp1_b32 s29, 0
	s_cselect_b32 s30, 0x6000, 0
	s_add_i32 s22, s31, 2
	v_add_u32_e32 v156, s30, v203
	v_cmp_lt_u32_e32 vcc, s22, v185
	s_waitcnt vmcnt(1)
	ds_write_b128 v156, v[128:131]
	ds_write_b128 v156, v[132:135] offset:8192
	s_waitcnt vmcnt(0)
	ds_write_b128 v156, v[136:139] offset:16384
	s_and_saveexec_b64 s[22:23], vcc
	s_cbranch_execz .Ldf_noload
	global_load_dwordx4 v[128:131], v[174:175], off
	global_load_dwordx4 v[132:135], v[170:171], off
	global_load_dwordx4 v[136:139], v[172:173], off
; #define MFMA(a, b, c) __builtin_amdgcn_mfma_f32_32x32x16_bf16((a), (b), (c), 0, 0, 0)
; template <int DV, bool NA> ...
;     ...
;       {
;         bf16x8 ka[4], kb_[4];
; #pragma unroll
;         for (int ks = 0; ks < 4; ++ks) {
;           const int co = ((2 * ks + h) ^ ksw) << 4;
;           ka[ks] = *(const bf16x8*)(st + pr * 128 + co);
;           kb_[ks] = *(const bf16x8*)(st + (32 + pr) * 128 + co);
;         }
;         asm volatile("" ::: "memory");
; #pragma unroll
;         for (int ks = 0; ks < 4; ++ks) {
;           s0 = MFMA(ka[ks], q[ks], s0);
;           s1 = MFMA(kb_[ks], q[ks], s1);
;         }
;       }
;     ...
;       float mx = t[0];
; #pragma unroll
;       for (int e = 1; e < 32; ++e) mx = fmaxf(mx, t[e]);
;       mx = fmaxf(mx, __shfl_xor(mx, 32));
;       if (__builtin_amdgcn_ballot_w64(mx > m_run + 8.f) != 0ull) {
;         const float m_new = fmaxf(m_run, mx);
;         const float alpha = fexp2(m_run - m_new);
;         l_run *= alpha;
;         m_run = m_new;
; #pragma unroll
;         for (int mv = 0; mv < DV / 32; ++mv)
; #pragma unroll
;           for (int i = 0; i < 16; ++i) o[mv][i] *= alpha;
;       }
;       float ls = 0.f;
; #pragma unroll
;       for (int e = 0; e < 32; ++e) { t[e] = fexp2(t[e] - m_run); ls += t[e]; }
;       l_run += ls;
;       bf16x8 pf[2][2];
; #pragma unroll
;       for (int kb = 0; kb < 2; ++kb)
; #pragma unroll
;         for (int c2 = 0; c2 < 2; ++c2) {
;           const int e0 = kb * 16 + c2 * 8;
;           u32x4 pw = {pk_bf16(t[e0], t[e0 + 1]), pk_bf16(t[e0 + 2], t[e0 + 3]), pk_bf16(t[e0 + 4], t[e0 + 5]), pk_bf16(t[e0 + 6], t[e0 + 7])};
;           pf[kb][c2] = __builtin_bit_cast(bf16x8, pw);
;         }
;       bf16x8 vf1[2][DV / 32];
; #pragma unroll
;       for (int c2 = 0; c2 < 2; ++c2) {
;         const int co = ((4 + 2 * c2 + h) ^ vsw) << 4;
; #pragma unroll
;         for (int mv = 0; mv < DV / 32; ++mv) vf1[c2][mv] = *(const bf16x8*)(st + 8192 + (mv * 32 + r) * 128 + co);
;       }
;       asm volatile("" ::: "memory");
; #pragma unroll
;       for (int c2 = 0; c2 < 2; ++c2)
; #pragma unroll
;         for (int mv = 0; mv < DV / 32; ++mv) o[mv] = MFMA(vf0[c2][mv], pf[0][c2], o[mv]);
; #pragma unroll
;       for (int c2 = 0; c2 < 2; ++c2)
; #pragma unroll
;         for (int mv = 0; mv < DV / 32; ++mv) o[mv] = MFMA(vf1[c2][mv], pf[1][c2], o[mv]);
;     }
;     __syncthreads();
.Ldf_noload:
	s_or_b64 exec, exec, s[22:23]
	s_bitcmp1_b32 s31, 0
	s_cselect_b32 s22, 0x6000, 0
	v_add_u32_e32 v156, s22, v228
	v_add3_u32 v230, s22, v195, v178
	v_add_u32_e32 v157, v156, v229
	v_add_u32_e32 v158, v156, v202
	ds_read_b128 v[0:3], v157
	ds_read_b128 v[4:7], v157 offset:4096
	ds_read_b128 v[8:11], v158
	ds_read_b128 v[12:15], v158 offset:4096
	v_add_u32_e32 v157, v156, v201
	v_add_u32_e32 v158, v156, v200
	v_add3_u32 v231, s22, v183, v178
	s_waitcnt lgkmcnt(3)
	v_mfma_f32_32x32x16_bf16 v[96:111], v[0:3], v[124:127], v[234:249]
	s_waitcnt lgkmcnt(2)
	v_mfma_f32_32x32x16_bf16 v[80:95], v[4:7], v[124:127], v[234:249]
	ds_read_b128 v[0:3], v157
	ds_read_b128 v[4:7], v157 offset:4096
	s_waitcnt lgkmcnt(3)
	v_mfma_f32_32x32x16_bf16 v[96:111], v[8:11], v[120:123], v[96:111]
	s_waitcnt lgkmcnt(2)
	v_mfma_f32_32x32x16_bf16 v[80:95], v[12:15], v[120:123], v[80:95]
	ds_read_b128 v[8:11], v158
	ds_read_b128 v[12:15], v158 offset:4096
	ds_read_b128 v[140:143], v230 offset:8192
	ds_read_b128 v[144:147], v230 offset:12288
	ds_read_b128 v[148:151], v230 offset:16384
	ds_read_b128 v[152:155], v230 offset:20480
	s_waitcnt lgkmcnt(7)
	v_mfma_f32_32x32x16_bf16 v[96:111], v[0:3], v[116:119], v[96:111]
	s_waitcnt lgkmcnt(6)
	v_mfma_f32_32x32x16_bf16 v[80:95], v[4:7], v[116:119], v[80:95]
	s_waitcnt lgkmcnt(5)
	v_mfma_f32_32x32x16_bf16 v[96:111], v[8:11], v[112:115], v[96:111]
	s_waitcnt lgkmcnt(4)
	v_mfma_f32_32x32x16_bf16 v[80:95], v[12:15], v[112:115], v[80:95]
	ds_read_b128 v[0:3], v231 offset:8192
	ds_read_b128 v[4:7], v231 offset:12288
	ds_read_b128 v[8:11], v231 offset:16384
	ds_read_b128 v[12:15], v231 offset:20480
	v_cmp_eq_u32_e32 vcc, s29, v177
	v_lshl_add_u64 v[170:171], v[170:171], 0, s[4:5]
	v_lshl_add_u64 v[172:173], v[172:173], 0, s[4:5]
	v_lshl_add_u64 v[174:175], v[174:175], 0, s[82:83]
	s_mov_b32 s31, s29
	s_or_b64 s[20:21], vcc, s[20:21]
	v_max3_f32 v156, v96, v97, v98
	v_max3_f32 v157, v105, v106, v107
	v_max3_f32 v158, v80, v81, v82
	v_max3_f32 v159, v89, v90, v91
	v_max3_f32 v156, v156, v99, v100
	v_max3_f32 v157, v157, v108, v109
	v_max3_f32 v158, v158, v83, v84
	v_max3_f32 v159, v159, v92, v93
	v_max3_f32 v156, v156, v101, v102
	v_max3_f32 v157, v157, v110, v111
	v_max3_f32 v158, v158, v85, v86
	v_max3_f32 v159, v159, v94, v95
	v_max3_f32 v156, v156, v103, v104
	v_max3_f32 v158, v158, v87, v88
	v_max3_f32 v156, v156, v157, v158
	v_max_f32_e32 v156, v156, v159
	v_mov_b32_e32 v157, v156
	v_add3_u32 v210, s22, v181, v178
	s_nop 0
	v_permlane32_swap_b32_e32 v156, v157
	v_max_f32_e32 v156, v156, v157
	v_cmp_lt_f32_e32 vcc, s100, v156
	s_cbranch_vccnz .Ldf_rare
.Ldf_cont:
	v_exp_f32_e32 v96, v96
	v_exp_f32_e32 v97, v97
	v_exp_f32_e32 v98, v98
	v_exp_f32_e32 v99, v99
	v_exp_f32_e32 v100, v100
	v_exp_f32_e32 v101, v101
	v_exp_f32_e32 v102, v102
	v_exp_f32_e32 v103, v103
	v_cvt_pk_bf16_f32 v156, v96, v97
	v_cvt_pk_bf16_f32 v157, v98, v99
	v_cvt_pk_bf16_f32 v158, v100, v101
	v_cvt_pk_bf16_f32 v159, v102, v103
	v_exp_f32_e32 v104, v104
	v_exp_f32_e32 v105, v105
	s_waitcnt lgkmcnt(4)
	v_mfma_f32_32x32x16_bf16 v[64:79], v[140:143], v[156:159], v[64:79]
	v_exp_f32_e32 v106, v106
	v_exp_f32_e32 v107, v107
	v_add_f32_e32 v96, v96, v97
	v_mfma_f32_32x32x16_bf16 v[48:63], v[144:147], v[156:159], v[48:63]
	v_exp_f32_e32 v108, v108
	v_exp_f32_e32 v109, v109
	v_add_f32_e32 v98, v98, v99
	v_mfma_f32_32x32x16_bf16 v[32:47], v[148:151], v[156:159], v[32:47]
	v_exp_f32_e32 v110, v110
	v_exp_f32_e32 v111, v111
	v_add_f32_e32 v100, v100, v101
	v_mfma_f32_32x32x16_bf16 v[16:31], v[152:155], v[156:159], v[16:31]
	ds_read_b128 v[140:143], v210 offset:8192
	ds_read_b128 v[144:147], v210 offset:12288
	ds_read_b128 v[148:151], v210 offset:16384
	ds_read_b128 v[152:155], v210 offset:20480
	v_add3_u32 v210, s22, v179, v178
	v_add_f32_e32 v102, v102, v103
	v_cvt_pk_bf16_f32 v230, v104, v105
	v_cvt_pk_bf16_f32 v231, v106, v107
	v_cvt_pk_bf16_f32 v232, v108, v109
	v_cvt_pk_bf16_f32 v233, v110, v111
	v_add_f32_e32 v96, v96, v98
	v_add_f32_e32 v100, v100, v102
	v_exp_f32_e32 v80, v80
	v_exp_f32_e32 v81, v81
	s_waitcnt lgkmcnt(4)
	v_mfma_f32_32x32x16_bf16 v[64:79], v[0:3], v[230:233], v[64:79]
	v_exp_f32_e32 v82, v82
	v_exp_f32_e32 v83, v83
	v_add_f32_e32 v104, v104, v105
	v_add_f32_e32 v96, v96, v100
	v_mfma_f32_32x32x16_bf16 v[48:63], v[4:7], v[230:233], v[48:63]
	v_exp_f32_e32 v84, v84
	v_exp_f32_e32 v85, v85
	v_add_f32_e32 v106, v106, v107
	v_add_f32_e32 v180, v180, v96
	v_mfma_f32_32x32x16_bf16 v[32:47], v[8:11], v[230:233], v[32:47]
	v_exp_f32_e32 v86, v86
	v_exp_f32_e32 v87, v87
	v_add_f32_e32 v108, v108, v109
	v_mfma_f32_32x32x16_bf16 v[16:31], v[12:15], v[230:233], v[16:31]
	ds_read_b128 v[0:3], v210 offset:8192
	ds_read_b128 v[4:7], v210 offset:12288
	ds_read_b128 v[8:11], v210 offset:16384
	ds_read_b128 v[12:15], v210 offset:20480
	v_add_f32_e32 v110, v110, v111
	v_cvt_pk_bf16_f32 v156, v80, v81
	v_cvt_pk_bf16_f32 v157, v82, v83
	v_cvt_pk_bf16_f32 v158, v84, v85
	v_cvt_pk_bf16_f32 v159, v86, v87
	v_add_f32_e32 v104, v104, v106
	v_add_f32_e32 v108, v108, v110
	v_exp_f32_e32 v88, v88
	v_exp_f32_e32 v89, v89
	s_waitcnt lgkmcnt(4)
	v_mfma_f32_32x32x16_bf16 v[64:79], v[140:143], v[156:159], v[64:79]
	v_exp_f32_e32 v90, v90
	v_exp_f32_e32 v91, v91
	v_add_f32_e32 v80, v80, v81
	v_add_f32_e32 v104, v104, v108
	v_mfma_f32_32x32x16_bf16 v[48:63], v[144:147], v[156:159], v[48:63]
	v_exp_f32_e32 v92, v92
	v_exp_f32_e32 v93, v93
	v_add_f32_e32 v82, v82, v83
	v_add_f32_e32 v180, v180, v104
	v_mfma_f32_32x32x16_bf16 v[32:47], v[148:151], v[156:159], v[32:47]
	v_exp_f32_e32 v94, v94
	v_exp_f32_e32 v95, v95
	v_add_f32_e32 v84, v84, v85
	v_mfma_f32_32x32x16_bf16 v[16:31], v[152:155], v[156:159], v[16:31]
	v_add_f32_e32 v86, v86, v87
	v_cvt_pk_bf16_f32 v230, v88, v89
	v_cvt_pk_bf16_f32 v231, v90, v91
	v_cvt_pk_bf16_f32 v232, v92, v93
	v_cvt_pk_bf16_f32 v233, v94, v95
	v_add_f32_e32 v80, v80, v82
	v_add_f32_e32 v84, v84, v86
	s_waitcnt lgkmcnt(0)
	s_barrier
	v_mfma_f32_32x32x16_bf16 v[64:79], v[0:3], v[230:233], v[64:79]
	v_add_f32_e32 v88, v88, v89
	v_add_f32_e32 v80, v80, v84
	v_mfma_f32_32x32x16_bf16 v[48:63], v[4:7], v[230:233], v[48:63]
	v_add_f32_e32 v90, v90, v91
	v_add_f32_e32 v180, v180, v80
	v_mfma_f32_32x32x16_bf16 v[32:47], v[8:11], v[230:233], v[32:47]
	v_add_f32_e32 v92, v92, v93
	v_mfma_f32_32x32x16_bf16 v[16:31], v[12:15], v[230:233], v[16:31]
	v_add_f32_e32 v94, v94, v95
	v_add_f32_e32 v88, v88, v90
	v_add_f32_e32 v92, v92, v94
	v_add_f32_e32 v88, v88, v92
	v_mov_b32_e32 v0, s30
	v_mov_b32_e32 v1, 0
	v_add_f32_e32 v180, v180, v88
	s_andn2_b64 exec, exec, s[20:21]
	s_cbranch_execnz .LBB0_296
	s_branch .LBB0_300
; DI float fexp2(float x) { return __builtin_amdgcn_exp2f(x); }
; template <int DV, bool NA> ...
;     ...
;       if (__builtin_amdgcn_ballot_w64(mx > m_run + 8.f) != 0ull) {
;         const float m_new = fmaxf(m_run, mx);
;         const float alpha = fexp2(m_run - m_new);
;         l_run *= alpha;
;         m_run = m_new;
; #pragma unroll
;         for (int mv = 0; mv < DV / 32; ++mv)
; #pragma unroll
;           for (int i = 0; i < 16; ++i) o[mv][i] *= alpha;
;       }
.Ldf_rare:
	v_max_f32_e32 v157, s101, v156
	s_mov_b32 s100, 0x41000000
	s_mov_b32 s101, 0
	v_add_f32_e32 v182, v182, v157
	v_min_f32_e64 v158, -v157, 0
	v_exp_f32_e32 v158, v158
	v_sub_f32_e32 v234, v234, v157
	v_sub_f32_e32 v235, v235, v157
	v_sub_f32_e32 v236, v236, v157
	v_sub_f32_e32 v237, v237, v157
	v_sub_f32_e32 v238, v238, v157
	v_sub_f32_e32 v239, v239, v157
	v_sub_f32_e32 v240, v240, v157
	v_sub_f32_e32 v241, v241, v157
	v_sub_f32_e32 v242, v242, v157
	v_sub_f32_e32 v243, v243, v157
	v_sub_f32_e32 v244, v244, v157
	v_sub_f32_e32 v245, v245, v157
	v_sub_f32_e32 v246, v246, v157
	v_sub_f32_e32 v247, v247, v157
	v_sub_f32_e32 v248, v248, v157
	v_sub_f32_e32 v249, v249, v157
	v_sub_f32_e32 v80, v80, v157
	v_sub_f32_e32 v81, v81, v157
	v_sub_f32_e32 v82, v82, v157
	v_sub_f32_e32 v83, v83, v157
	v_sub_f32_e32 v84, v84, v157
	v_sub_f32_e32 v85, v85, v157
	v_sub_f32_e32 v86, v86, v157
	v_sub_f32_e32 v87, v87, v157
	v_sub_f32_e32 v88, v88, v157
	v_sub_f32_e32 v89, v89, v157
	v_sub_f32_e32 v90, v90, v157
	v_sub_f32_e32 v91, v91, v157
	v_sub_f32_e32 v92, v92, v157
	v_sub_f32_e32 v93, v93, v157
	v_sub_f32_e32 v94, v94, v157
	v_sub_f32_e32 v95, v95, v157
	v_sub_f32_e32 v96, v96, v157
	v_sub_f32_e32 v97, v97, v157
	v_sub_f32_e32 v98, v98, v157
	v_sub_f32_e32 v99, v99, v157
	v_sub_f32_e32 v100, v100, v157
	v_sub_f32_e32 v101, v101, v157
	v_sub_f32_e32 v102, v102, v157
	v_sub_f32_e32 v103, v103, v157
	v_sub_f32_e32 v104, v104, v157
	v_sub_f32_e32 v105, v105, v157
	v_sub_f32_e32 v106, v106, v157
	v_sub_f32_e32 v107, v107, v157
	v_sub_f32_e32 v108, v108, v157
	v_sub_f32_e32 v109, v109, v157
	v_sub_f32_e32 v110, v110, v157
	v_sub_f32_e32 v111, v111, v157
	v_pk_mul_f32 v[16:17], v[16:17], v[158:159] op_sel_hi:[1,0]
	v_pk_mul_f32 v[18:19], v[18:19], v[158:159] op_sel_hi:[1,0]
	v_pk_mul_f32 v[20:21], v[20:21], v[158:159] op_sel_hi:[1,0]
	v_pk_mul_f32 v[22:23], v[22:23], v[158:159] op_sel_hi:[1,0]
	v_pk_mul_f32 v[24:25], v[24:25], v[158:159] op_sel_hi:[1,0]
	v_pk_mul_f32 v[26:27], v[26:27], v[158:159] op_sel_hi:[1,0]
	v_pk_mul_f32 v[28:29], v[28:29], v[158:159] op_sel_hi:[1,0]
	v_pk_mul_f32 v[30:31], v[30:31], v[158:159] op_sel_hi:[1,0]
	v_pk_mul_f32 v[32:33], v[32:33], v[158:159] op_sel_hi:[1,0]
	v_pk_mul_f32 v[34:35], v[34:35], v[158:159] op_sel_hi:[1,0]
	v_pk_mul_f32 v[36:37], v[36:37], v[158:159] op_sel_hi:[1,0]
	v_pk_mul_f32 v[38:39], v[38:39], v[158:159] op_sel_hi:[1,0]
	v_pk_mul_f32 v[40:41], v[40:41], v[158:159] op_sel_hi:[1,0]
	v_pk_mul_f32 v[42:43], v[42:43], v[158:159] op_sel_hi:[1,0]
	v_pk_mul_f32 v[44:45], v[44:45], v[158:159] op_sel_hi:[1,0]
	v_pk_mul_f32 v[46:47], v[46:47], v[158:159] op_sel_hi:[1,0]
	v_pk_mul_f32 v[48:49], v[48:49], v[158:159] op_sel_hi:[1,0]
	v_pk_mul_f32 v[50:51], v[50:51], v[158:159] op_sel_hi:[1,0]
	v_pk_mul_f32 v[52:53], v[52:53], v[158:159] op_sel_hi:[1,0]
	v_pk_mul_f32 v[54:55], v[54:55], v[158:159] op_sel_hi:[1,0]
	v_pk_mul_f32 v[56:57], v[56:57], v[158:159] op_sel_hi:[1,0]
	v_pk_mul_f32 v[58:59], v[58:59], v[158:159] op_sel_hi:[1,0]
	v_pk_mul_f32 v[60:61], v[60:61], v[158:159] op_sel_hi:[1,0]
	v_pk_mul_f32 v[62:63], v[62:63], v[158:159] op_sel_hi:[1,0]
	v_pk_mul_f32 v[64:65], v[64:65], v[158:159] op_sel_hi:[1,0]
	v_pk_mul_f32 v[66:67], v[66:67], v[158:159] op_sel_hi:[1,0]
	v_pk_mul_f32 v[68:69], v[68:69], v[158:159] op_sel_hi:[1,0]
	v_pk_mul_f32 v[70:71], v[70:71], v[158:159] op_sel_hi:[1,0]
	v_pk_mul_f32 v[72:73], v[72:73], v[158:159] op_sel_hi:[1,0]
	v_pk_mul_f32 v[74:75], v[74:75], v[158:159] op_sel_hi:[1,0]
	v_pk_mul_f32 v[76:77], v[76:77], v[158:159] op_sel_hi:[1,0]
	v_pk_mul_f32 v[78:79], v[78:79], v[158:159] op_sel_hi:[1,0]
	v_mul_f32_e32 v180, v180, v158
	s_branch .Ldf_cont

; __global__ void __launch_bounds__(NTHR) mega(Params p, int ph0, int ph1) {
;   __shared__ __attribute__((aligned(16))) char lds[LDS_BYTES];
	.amdhsa_kernel _Z4mega6Paramsii
		.amdhsa_group_segment_fixed_size 133120
		.amdhsa_private_segment_fixed_size 0
		.amdhsa_kernarg_size 440
		.amdhsa_user_sgpr_count 2
		.amdhsa_user_sgpr_dispatch_ptr 0
		.amdhsa_user_sgpr_queue_ptr 0
		.amdhsa_user_sgpr_kernarg_segment_ptr 1
		.amdhsa_user_sgpr_dispatch_id 0
		.amdhsa_user_sgpr_kernarg_preload_length 0
		.amdhsa_user_sgpr_kernarg_preload_offset 0
		.amdhsa_user_sgpr_private_segment_size 0
		.amdhsa_uses_dynamic_stack 0
		.amdhsa_enable_private_segment 0
		.amdhsa_system_sgpr_workgroup_id_x 1
		.amdhsa_system_sgpr_workgroup_id_y 0
		.amdhsa_system_sgpr_workgroup_id_z 0
		.amdhsa_system_sgpr_workgroup_info 0
		.amdhsa_system_vgpr_workitem_id 2
		.amdhsa_next_free_vgpr 256
		.amdhsa_next_free_sgpr 102
		.amdhsa_accum_offset 256
		.amdhsa_reserve_vcc 1
		.amdhsa_float_round_mode_32 0
		.amdhsa_float_round_mode_16_64 0
		.amdhsa_float_denorm_mode_32 3
		.amdhsa_float_denorm_mode_16_64 3
		.amdhsa_dx10_clamp 1
		.amdhsa_ieee_mode 1
		.amdhsa_fp16_overflow 0
		.amdhsa_tg_split 0
		.amdhsa_exception_fp_ieee_invalid_op 0
		.amdhsa_exception_fp_denorm_src 0
		.amdhsa_exception_fp_ieee_div_zero 0
		.amdhsa_exception_fp_ieee_overflow 0
		.amdhsa_exception_fp_ieee_underflow 0
		.amdhsa_exception_fp_ieee_inexact 0
		.amdhsa_exception_int_div_zero 0
	.end_amdhsa_kernel

; __global__ void __launch_bounds__(NTHR) mega(Params p, int ph0, int ph1) {
;   __shared__ __attribute__((aligned(16))) char lds[LDS_BYTES];
amdhsa.kernels:
  - .agpr_count:     0
    .args:
      - .offset:         0
        .size:           176
        .value_kind:     by_value
      - .offset:         176
        .size:           4
        .value_kind:     by_value
      - .offset:         180
        .size:           4
        .value_kind:     by_value
      - .offset:         184
        .size:           4
        .value_kind:     hidden_block_count_x
      - .offset:         188
        .size:           4
        .value_kind:     hidden_block_count_y
      - .offset:         192
        .size:           4
        .value_kind:     hidden_block_count_z
      - .offset:         196
        .size:           2
        .value_kind:     hidden_group_size_x
      - .offset:         198
        .size:           2
        .value_kind:     hidden_group_size_y
      - .offset:         200
        .size:           2
        .value_kind:     hidden_group_size_z
      - .offset:         202
        .size:           2
        .value_kind:     hidden_remainder_x
      - .offset:         204
        .size:           2
        .value_kind:     hidden_remainder_y
      - .offset:         206
        .size:           2
        .value_kind:     hidden_remainder_z
      - .offset:         224
        .size:           8
        .value_kind:     hidden_global_offset_x
      - .offset:         232
        .size:           8
        .value_kind:     hidden_global_offset_y
      - .offset:         240
        .size:           8
        .value_kind:     hidden_global_offset_z
      - .offset:         248
        .size:           2
        .value_kind:     hidden_grid_dims
      - .offset:         272
        .size:           8
        .value_kind:     hidden_multigrid_sync_arg
    .group_segment_fixed_size: 133120
    .kernarg_segment_align: 8
    .kernarg_segment_size: 440
    .language:       OpenCL C
    .language_version:
      - 2
      - 0
    .max_flat_workgroup_size: 512
    .name:           _Z4mega6Paramsii
    .private_segment_fixed_size: 0
    .sgpr_count:     108
    .sgpr_spill_count: 144
    .symbol:         _Z4mega6Paramsii.kd
    .uniform_work_group_size: 1
    .uses_dynamic_stack: false
    .vgpr_count:     256
    .vgpr_spill_count: 0
    .wavefront_size: 64
